# mLSTM walk: next-step load addresses precomputed at step top
# baseline (speedup 1.0000x reference)
.LBB0_512:
	v_add_u32_e32 v196, 1, v52
	v_cmp_lt_i32_e32 vcc, v196, v193
	s_cbranch_vccz .Lml_pre_done
	v_cmp_gt_i32_e32 vcc, 3, v52
	s_nop 1
	v_cndmask_b32_e64 v46, v217, 3, vcc
	v_add3_u32 v46, v194, v46, s18
	v_subrev_u32_e32 v46, 45, v46
	v_cndmask_b32_e64 v46, v46, v196, s[62:63]
	v_add_u32_e32 v93, v46, v192
	v_mul_hi_i32 v46, v93, s7
	v_lshrrev_b32_e32 v47, 31, v46
	v_ashrrev_i32_e32 v46, 5, v46
	v_add_u32_e32 v46, v46, v47
	v_mul_lo_u32 v47, v46, s17
	v_sub_u32_e32 v47, v93, v47
	v_cmp_lt_i32_e32 vcc, 3, v47
	v_lshlrev_b32_e32 v47, 6, v47
	v_lshlrev_b32_e32 v48, 13, v46
	v_lshlrev_b32_e32 v49, 8, v46
	s_movk_i32 s19, 0xff00
	v_add3_u32 v48, v47, v48, s19
	s_mov_b32 s19, 0x8000
	v_add3_u32 v49, v49, v47, s19
	v_cndmask_b32_e32 v197, v49, v48, vcc
	v_mov_b64_e32 v[46:47], s[70:71]
	v_mad_i64_i32 v[50:51], s[14:15], v197, s74, v[46:47]
	v_mov_b32_e32 v47, v1
	v_lshl_add_u64 v[198:199], v[50:51], 0, v[0:1]
	v_mov_b32_e32 v46, v84
	v_lshl_add_u64 v[200:201], v[50:51], 0, v[46:47]
	v_mov_b32_e32 v46, v86
	v_lshl_add_u64 v[202:203], v[50:51], 0, v[46:47]
	v_mov_b32_e32 v46, v90
	v_lshl_add_u64 v[204:205], v[50:51], 0, v[46:47]
	v_mov_b32_e32 v46, v92
	v_lshl_add_u64 v[204:205], v[204:205], 0, v[46:47]
	v_lshl_add_u64 v[204:205], v[88:89], 1, v[204:205]
	v_mov_b32_e32 v46, v94
	v_lshl_add_u64 v[204:205], v[204:205], 0, v[46:47]
	v_add_co_u32_e32 v204, vcc, 0x1000, v204
	s_nop 1
	v_addc_co_u32_e32 v205, vcc, 0, v205, vcc
	v_add_u32_e32 v46, v197, v187
	v_ashrrev_i32_e32 v47, 31, v46
	v_lshlrev_b64 v[46:47], 7, v[46:47]
	v_lshl_add_u64 v[234:235], v[102:103], 0, v[46:47]
	v_lshl_add_u32 v93, v93, 1, v188
	v_lshl_or_b32 v46, v93, 3, v189
	v_ashrrev_i32_e32 v47, 31, v46
	v_lshl_add_u64 v[236:237], v[46:47], 2, s[86:87]
	v_add_u32_e32 v46, v197, v190
	v_ashrrev_i32_e32 v47, 31, v46
	v_lshl_add_u64 v[46:47], v[46:47], 3, v[98:99]
	v_lshl_add_u64 v[238:239], v[46:47], 4, s[90:91]
	v_lshl_add_u64 v[240:241], v[46:47], 2, s[88:89]
	v_ashrrev_i32_e32 v47, 31, v93
	v_mov_b32_e32 v46, v93
	v_lshlrev_b64 v[46:47], 2, v[46:47]
	v_or_b32_e32 v46, v46, v83
	s_movk_i32 s19, 0x180
	v_mad_u64_u32 v[242:243], s[14:15], v46, s19, v[76:77]
	v_mad_i32_i24 v243, v47, s19, v243
	v_add_u32_e32 v46, v197, v191
	v_mad_i64_i32 v[244:245], s[14:15], v46, s16, v[100:101]

.LBB0_524:
	s_or_b64 exec, exec, s[10:11]
	v_add_u32_e32 v196, 1, v52
	v_cmp_lt_i32_e32 vcc, v196, v193
	v_mov_b32_e32 v91, v96
	v_mov_b64_e32 v[108:109], v[104:105]
	v_mov_b64_e32 v[110:111], v[106:107]
	s_and_saveexec_b64 s[10:11], vcc
	s_cbranch_execz .LBB0_541
	s_and_b64 vcc, exec, s[60:61]
	s_cbranch_vccnz .Lml_ld_a
	global_load_dwordx4 v[14:17], v[198:199], off offset:2880
.Lml_ld_a:
	global_load_dwordx4 v[26:29], v[198:199], off offset:3648
	s_cbranch_vccnz .Lml_ld_b
	global_load_dwordx4 v[18:21], v[200:201], off offset:2880
.Lml_ld_b:
	global_load_dwordx4 v[30:33], v[200:201], off offset:3648
	s_cbranch_vccnz .Lml_ld_c
	global_load_dwordx4 v[22:25], v[202:203], off offset:2880
.Lml_ld_c:
	global_load_dwordx4 v[38:41], v[202:203], off offset:3648
	global_load_dwordx4 v[42:45], v[204:205], off offset:320
	global_load_dword v85, v[234:235], off offset:12
	global_load_dword v87, v[236:237], off offset:4
	s_and_saveexec_b64 s[14:15], s[52:53]
	s_cbranch_execz .LBB0_537
	global_load_dwordx4 v[34:37], v[238:239], off
	s_nop 0
	global_load_dword v35, v[240:241], off
	global_load_dword v37, v[236:237], off
.LBB0_537:
	s_or_b64 exec, exec, s[14:15]
	v_mov_b32_e32 v91, v96
	s_and_saveexec_b64 s[14:15], s[50:51]
	s_cbranch_execz .LBB0_539
	global_load_dword v91, v[242:243], off
.LBB0_539:
	s_or_b64 exec, exec, s[14:15]
	s_and_b64 vcc, exec, s[60:61]
	v_mov_b64_e32 v[108:109], v[104:105]
	v_mov_b64_e32 v[110:111], v[106:107]
	s_cbranch_vccnz .LBB0_541
	global_load_dwordx2 v[110:111], v[244:245], off
	global_load_dwordx2 v[108:109], v[244:245], off offset:32
